# attention group prologue: all global loads and the 11 key-tile LDS-DMA pairs issued in one round at the top of the group; window lengths exchanged through ds_write/ds_read instead of serialized flat a
# baseline (speedup 1.0000x reference)
; DI void fox_attn_blk(const Params& P, unsigned char* lds, LAS unsigned char* ldsl, int tid, int G, float PRUNE, int pir) {
;     ...
;         const int QB0 = grp * 8, qb = QB0 + wave, t0 = qb * 32, nq = qb >> 1;
;         bf16x8 qf[4];
; #pragma unroll
;         for (int ks = 0; ks < 4; ++ks) qf[ks] = *(const bf16x8*)(QN + (size_t)(t0 + r32) * 512 + h * 64 + 16 * ks + 8 * hi);
;         const float cq = CLh[t0 + r32];
;         const float cq0 = __uint_as_float(__builtin_amdgcn_readfirstlane(__float_as_uint(CLh[t0])));
;         float offv; int nvalid;
;         { const int cn = nq - 1 - lane; float pre = cn >= 0 ? CTh[cn] : 0.f;
;           const int kt = qb - 1 - lane; const float clen = kt >= 0 ? CLh[32 * kt + 31] : 0.f;
;     ...
;         for (int j_ = 0; j_ < 11; ++j_) DMA_TILE(QB0 + 7 - j_);
.LBB0_734:
	s_lshl_b32 s33, s3, 3
	v_add_u32_e32 v88, s33, v1
	v_lshlrev_b32_e32 v130, 5, v88
	v_or_b32_e32 v2, v130, v165
	v_ashrrev_i32_e32 v3, 31, v2
	v_lshlrev_b64 v[4:5], 10, v[2:3]
	v_lshl_add_u64 v[84:85], v[174:175], 0, v[4:5]
	global_load_dwordx4 v[50:53], v[84:85], off
	global_load_dwordx4 v[54:57], v[84:85], off offset:32
	v_lshl_add_u64 v[86:87], v[2:3], 2, s[64:65]
	v_ashrrev_i32_e32 v131, 31, v130
	v_lshl_add_u64 v[82:83], v[130:131], 2, s[64:65]
	global_load_dword v90, v[86:87], off
	global_load_dword v4, v[82:83], off
	global_load_dwordx4 v[58:61], v[84:85], off offset:64
	global_load_dwordx4 v[62:65], v[84:85], off offset:96
	v_ashrrev_i32_e32 v5, 1, v88
	v_add_u32_e32 v89, -1, v5
	v_sub_u32_e32 v170, v89, v163
	v_cmp_lt_i32_e64 s[54:55], -1, v170
	v_mov_b32_e32 v6, v171
	v_lshlrev_b64 v[194:195], 9, v[2:3]
	v_or_b32_e32 v194, s9, v194
	v_lshlrev_b64 v[254:255], 1, v[194:195]
	v_lshl_add_u64 v[254:255], v[186:187], 0, v[254:255]
	global_load_dwordx2 v[240:241], v[254:255], off
	global_load_dwordx2 v[242:243], v[254:255], off offset:16
	global_load_dwordx2 v[244:245], v[254:255], off offset:32
	global_load_dwordx2 v[246:247], v[254:255], off offset:48
	global_load_dwordx2 v[248:249], v[254:255], off offset:64
	global_load_dwordx2 v[250:251], v[254:255], off offset:80
	global_load_dwordx2 v[252:253], v[254:255], off offset:96
	global_load_dwordx2 v[254:255], v[254:255], off offset:112
	s_and_saveexec_b64 s[0:1], s[54:55]
	v_lshl_add_u64 v[118:119], v[170:171], 2, s[68:69]
	global_load_dword v6, v[118:119], off
	s_mov_b64 exec, s[0:1]
	v_add_u32_e32 v120, v88, v206
	v_mov_b32_e32 v121, 0
	v_cmp_lt_i32_e32 vcc, -1, v120
	s_and_saveexec_b64 s[0:1], vcc
	v_lshlrev_b32_e32 v118, 5, v120
	v_mov_b32_e32 v119, v171
	v_lshl_add_u64 v[118:119], v[118:119], 2, s[64:65]
	global_load_dword v121, v[118:119], off offset:124
	s_mov_b64 exec, s[0:1]
	s_or_b32 s0, s33, 7
	s_max_i32 s2, s0, 0
	s_add_i32 s0, s33, 0x7f
	s_mul_hi_i32 s1, s0, 0x2aaaaaab
	s_lshr_b32 s56, s1, 31
	s_lshr_b32 s1, s1, 1
	s_add_i32 s1, s1, s56
	s_mul_i32 s1, s1, 12
	s_sub_i32 s56, s0, s1
	v_mad_u64_u32 v[116:117], s[0:1], v168, s2, 0
	s_mulk_i32 s56, 0x2800
	s_add_i32 s0, s56, 0
	v_lshl_add_u64 v[116:117], v[116:117], 1, v[172:173]
	s_add_i32 m0, s0, s84
	s_add_i32 s0, s0, s85
	global_load_lds_dwordx4 v[116:117], off
	s_add_i32 m0, s0, 0x2000
	s_or_b32 s0, s33, 6
	s_lshl_b32 s62, s2, 5
	s_max_i32 s2, s0, 0
	s_add_i32 s0, s33, 0x7e
	s_mul_hi_i32 s1, s0, 0x2aaaaaab
	s_lshr_b32 s56, s1, 31
	s_lshr_b32 s1, s1, 1
	s_add_i32 s1, s1, s56
	s_mul_i32 s1, s1, 12
	v_lshl_add_u64 v[116:117], s[62:63], 2, v[166:167]
	s_sub_i32 s56, s0, s1
	global_load_lds_dword v[116:117], off
	v_mad_u64_u32 v[116:117], s[0:1], v168, s2, 0
	s_mulk_i32 s56, 0x2800
	s_add_i32 s0, s56, 0
	v_lshl_add_u64 v[116:117], v[116:117], 1, v[172:173]
	s_add_i32 m0, s0, s84
	s_add_i32 s0, s0, s85
	global_load_lds_dwordx4 v[116:117], off
	s_add_i32 m0, s0, 0x2000
	s_or_b32 s0, s33, 5
	s_lshl_b32 s62, s2, 5
	s_max_i32 s2, s0, 0
	s_add_i32 s0, s33, 0x7d
	s_mul_hi_i32 s1, s0, 0x2aaaaaab
	s_lshr_b32 s56, s1, 31
	s_lshr_b32 s1, s1, 1
	s_add_i32 s1, s1, s56
	s_mul_i32 s1, s1, 12
	v_lshl_add_u64 v[116:117], s[62:63], 2, v[166:167]
	s_sub_i32 s56, s0, s1
	global_load_lds_dword v[116:117], off
	v_mad_u64_u32 v[116:117], s[0:1], v168, s2, 0
	s_mulk_i32 s56, 0x2800
	s_add_i32 s0, s56, 0
	v_lshl_add_u64 v[116:117], v[116:117], 1, v[172:173]
	s_add_i32 m0, s0, s84
	s_add_i32 s0, s0, s85
	global_load_lds_dwordx4 v[116:117], off
	s_add_i32 m0, s0, 0x2000
	s_or_b32 s0, s33, 4
	s_lshl_b32 s62, s2, 5
	s_max_i32 s2, s0, 0
	s_add_i32 s0, s33, 0x7c
	s_mul_hi_i32 s1, s0, 0x2aaaaaab
	s_lshr_b32 s56, s1, 31
	s_lshr_b32 s1, s1, 1
	s_add_i32 s1, s1, s56
	s_mul_i32 s1, s1, 12
	v_lshl_add_u64 v[116:117], s[62:63], 2, v[166:167]
	s_sub_i32 s56, s0, s1
	global_load_lds_dword v[116:117], off
	v_mad_u64_u32 v[116:117], s[0:1], v168, s2, 0
	s_mulk_i32 s56, 0x2800
	s_add_i32 s0, s56, 0
	v_lshl_add_u64 v[116:117], v[116:117], 1, v[172:173]
	s_add_i32 m0, s0, s84
	s_add_i32 s0, s0, s85
	global_load_lds_dwordx4 v[116:117], off
	s_add_i32 m0, s0, 0x2000
	s_or_b32 s0, s33, 3
	s_lshl_b32 s62, s2, 5
	s_max_i32 s2, s0, 0
	s_add_i32 s0, s33, 0x7b
	s_mul_hi_i32 s1, s0, 0x2aaaaaab
	s_lshr_b32 s56, s1, 31
	s_lshr_b32 s1, s1, 1
	s_add_i32 s1, s1, s56
	s_mul_i32 s1, s1, 12
	v_lshl_add_u64 v[116:117], s[62:63], 2, v[166:167]
	s_sub_i32 s56, s0, s1
	global_load_lds_dword v[116:117], off
	v_mad_u64_u32 v[116:117], s[0:1], v168, s2, 0
	s_mulk_i32 s56, 0x2800
	s_add_i32 s0, s56, 0
	v_lshl_add_u64 v[116:117], v[116:117], 1, v[172:173]
	s_add_i32 m0, s0, s84
	s_add_i32 s0, s0, s85
	global_load_lds_dwordx4 v[116:117], off
	s_add_i32 m0, s0, 0x2000
	s_or_b32 s0, s33, 2
	s_lshl_b32 s62, s2, 5
	s_max_i32 s2, s0, 0
	s_add_i32 s0, s33, 0x7a
	s_mul_hi_i32 s1, s0, 0x2aaaaaab
	s_lshr_b32 s56, s1, 31
	s_lshr_b32 s1, s1, 1
	s_add_i32 s1, s1, s56
	s_mul_i32 s1, s1, 12
	v_lshl_add_u64 v[116:117], s[62:63], 2, v[166:167]
	s_sub_i32 s56, s0, s1
	global_load_lds_dword v[116:117], off
	v_mad_u64_u32 v[116:117], s[0:1], v168, s2, 0
	s_mulk_i32 s56, 0x2800
	s_add_i32 s0, s56, 0
	v_lshl_add_u64 v[116:117], v[116:117], 1, v[172:173]
	s_add_i32 m0, s0, s84
	s_add_i32 s0, s0, s85
	global_load_lds_dwordx4 v[116:117], off
	s_add_i32 m0, s0, 0x2000
	s_or_b32 s0, s33, 1
	s_lshl_b32 s62, s2, 5
	s_max_i32 s2, s0, 0
	s_add_i32 s0, s33, 0x79
	s_mul_hi_i32 s1, s0, 0x2aaaaaab
	s_lshr_b32 s56, s1, 31
	s_lshr_b32 s1, s1, 1
	s_add_i32 s1, s1, s56
	s_mul_i32 s1, s1, 12
	v_lshl_add_u64 v[116:117], s[62:63], 2, v[166:167]
	s_sub_i32 s56, s0, s1
	global_load_lds_dword v[116:117], off
; DI void fox_attn_blk(const Params& P, unsigned char* lds, LAS unsigned char* ldsl, int tid, int G, float PRUNE, int pir) {
;     ...
;         { const int cn = nq - 1 - lane; float pre = cn >= 0 ? CTh[cn] : 0.f;
;           const int kt = qb - 1 - lane; const float clen = kt >= 0 ? CLh[32 * kt + 31] : 0.f;
; #pragma unroll
;           for (int o = 1; o < 64; o <<= 1) { const float up = __shfl_up(pre, o); if (lane >= o) pre += up; }
;           const int nk = kt >> 1, src = nq - 1 - nk;
;           const float got = __shfl(pre, src < 0 ? 0 : src);
;           offv = (kt >= 0 && src >= 0) ? got : 0.f;
;           const float dmax = kt >= 0 ? cq0 + offv - clen : -INFINITY;
;           const unsigned long long stop = __ballot(dmax < -PRUNE || kt < 0);
;           nvalid = stop ? (int)__builtin_ctzll(stop) : 64; }
;         const size_t rowoff = (size_t)(t0 + r32) * 512 + h * 64;
;         if (lane == 0) nvs[wave] = nvalid;
;     ...
;         for (int j_ = 0; j_ < 11; ++j_) DMA_TILE(QB0 + 7 - j_);
	v_mad_u64_u32 v[116:117], s[0:1], v168, s2, 0
	s_mulk_i32 s56, 0x2800
	s_add_i32 s0, s56, 0
	v_lshl_add_u64 v[116:117], v[116:117], 1, v[172:173]
	s_add_i32 m0, s0, s84
	s_add_i32 s0, s0, s85
	global_load_lds_dwordx4 v[116:117], off
	s_add_i32 m0, s0, 0x2000
	s_add_i32 s0, s33, 0x78
	s_mul_hi_i32 s1, s0, 0x2aaaaaab
	s_lshr_b32 s56, s1, 31
	s_lshr_b32 s1, s1, 1
	s_add_i32 s1, s1, s56
	s_lshl_b32 s62, s2, 5
	s_mul_i32 s1, s1, 12
	v_lshl_add_u64 v[116:117], s[62:63], 2, v[166:167]
	s_max_i32 s2, s33, 0
	s_sub_i32 s56, s0, s1
	global_load_lds_dword v[116:117], off
	v_mad_u64_u32 v[116:117], s[0:1], v168, s2, 0
	s_mulk_i32 s56, 0x2800
	s_add_i32 s0, s56, 0
	v_lshl_add_u64 v[116:117], v[116:117], 1, v[172:173]
	s_add_i32 m0, s0, s84
	s_add_i32 s0, s0, s85
	global_load_lds_dwordx4 v[116:117], off
	s_add_i32 m0, s0, 0x2000
	s_max_i32 s0, s33, 1
	s_lshl_b32 s62, s2, 5
	s_add_i32 s2, s0, -1
	s_add_i32 s0, s33, 0x77
	s_mul_hi_i32 s1, s0, 0x2aaaaaab
	s_lshr_b32 s56, s1, 31
	s_lshr_b32 s1, s1, 1
	s_add_i32 s1, s1, s56
	s_mul_i32 s1, s1, 12
	v_lshl_add_u64 v[116:117], s[62:63], 2, v[166:167]
	s_sub_i32 s56, s0, s1
	global_load_lds_dword v[116:117], off
	v_mad_u64_u32 v[116:117], s[0:1], v168, s2, 0
	s_mulk_i32 s56, 0x2800
	s_add_i32 s0, s56, 0
	v_lshl_add_u64 v[116:117], v[116:117], 1, v[172:173]
	s_add_i32 m0, s0, s84
	s_add_i32 s0, s0, s85
	global_load_lds_dwordx4 v[116:117], off
	s_add_i32 m0, s0, 0x2000
	s_max_i32 s0, s33, 2
	s_lshl_b32 s62, s2, 5
	s_add_i32 s2, s0, -2
	s_add_i32 s0, s33, 0x76
	s_mul_hi_i32 s1, s0, 0x2aaaaaab
	s_lshr_b32 s56, s1, 31
	s_lshr_b32 s1, s1, 1
	s_add_i32 s1, s1, s56
	s_mul_i32 s1, s1, 12
	v_lshl_add_u64 v[116:117], s[62:63], 2, v[166:167]
	s_sub_i32 s56, s0, s1
	global_load_lds_dword v[116:117], off
	v_mad_u64_u32 v[116:117], s[0:1], v168, s2, 0
	s_mulk_i32 s56, 0x2800
	s_add_i32 s0, s56, 0
	v_lshl_add_u64 v[116:117], v[116:117], 1, v[172:173]
	s_add_i32 m0, s0, s84
	s_add_i32 s0, s0, s85
	global_load_lds_dwordx4 v[116:117], off
	s_add_i32 m0, s0, 0x2000
	s_max_i32 s0, s33, 3
	s_lshl_b32 s62, s2, 5
	s_add_i32 s2, s0, -3
	s_add_i32 s0, s33, 0x75
	s_mul_hi_i32 s1, s0, 0x2aaaaaab
	s_lshr_b32 s56, s1, 31
	s_lshr_b32 s1, s1, 1
	s_add_i32 s1, s1, s56
	s_mul_i32 s1, s1, 12
	v_lshl_add_u64 v[116:117], s[62:63], 2, v[166:167]
	s_sub_i32 s56, s0, s1
	global_load_lds_dword v[116:117], off
	v_mad_u64_u32 v[116:117], s[0:1], v168, s2, 0
	s_mulk_i32 s56, 0x2800
	s_add_i32 s0, s56, 0
	v_lshl_add_u64 v[116:117], v[116:117], 1, v[172:173]
	s_add_i32 m0, s0, s84
	s_lshl_b32 s62, s2, 5
	s_add_i32 s0, s0, s85
	global_load_lds_dwordx4 v[116:117], off
	v_lshl_add_u64 v[116:117], s[62:63], 2, v[166:167]
	s_add_i32 m0, s0, 0x2000
	global_load_lds_dword v[116:117], off
	s_waitcnt vmcnt(22)
	v_readfirstlane_b32 s2, v4
	v_mov_b32_e32 v4, v120
	v_mov_b32_e32 v5, v121
	v_cmp_lt_i32_e32 vcc, -1, v4
	ds_bpermute_b32 v7, v208, v6
	s_waitcnt lgkmcnt(0)
	v_add_f32_e32 v7, v6, v7
	v_cndmask_b32_e64 v6, v7, v6, s[6:7]
	ds_bpermute_b32 v7, v209, v6
	s_waitcnt lgkmcnt(0)
	v_add_f32_e32 v7, v6, v7
	v_cndmask_b32_e64 v6, v7, v6, s[10:11]
	ds_bpermute_b32 v7, v210, v6
	s_waitcnt lgkmcnt(0)
	v_add_f32_e32 v7, v6, v7
	v_cndmask_b32_e64 v6, v7, v6, s[12:13]
	ds_bpermute_b32 v7, v211, v6
	s_waitcnt lgkmcnt(0)
	v_add_f32_e32 v7, v6, v7
	v_cndmask_b32_e64 v6, v7, v6, s[14:15]
	ds_bpermute_b32 v7, v212, v6
	s_waitcnt lgkmcnt(0)
	v_add_f32_e32 v7, v6, v7
	v_cndmask_b32_e64 v6, v7, v6, s[16:17]
	ds_bpermute_b32 v7, v213, v6
	s_waitcnt lgkmcnt(0)
	v_add_f32_e32 v7, v6, v7
	v_cndmask_b32_e64 v6, v7, v6, s[18:19]
	v_ashrrev_i32_e32 v7, 1, v4
	v_sub_u32_e32 v7, v89, v7
	v_max_i32_e32 v8, 0, v7
	v_and_or_b32 v8, v8, 63, v203
	v_lshlrev_b32_e32 v8, 2, v8
	ds_bpermute_b32 v6, v8, v6
	v_or_b32_e32 v7, v7, v4
	v_cmp_lt_i32_e64 s[0:1], -1, v7
	s_waitcnt lgkmcnt(0)
	s_nop 0
	v_cndmask_b32_e64 v91, 0, v6, s[0:1]
	v_add_f32_e32 v6, s2, v91
	v_sub_f32_e32 v5, v6, v5
	v_cndmask_b32_e32 v5, v223, v5, vcc
	v_cmp_lt_f32_e64 s[0:1], v5, -v205
	v_cmp_gt_i32_e32 vcc, 0, v4
	s_or_b64 s[0:1], vcc, s[0:1]
	v_cndmask_b32_e64 v4, 0, 1, s[0:1]
	v_cmp_ne_u32_e32 vcc, 0, v4
	s_ff1_i32_b64 s0, vcc
	s_min_u32 s4, s0, 64
	s_and_saveexec_b64 s[0:1], s[6:7]
	s_cbranch_execz .LBB0_740
	v_mov_b32_e32 v4, s4
	v_lshlrev_b32_e32 v5, 2, v1
	v_add_u32_e32 v5, 0x1e000, v5
	ds_write_b32 v5, v4
; DI void fox_attn_blk(const Params& P, unsigned char* lds, LAS unsigned char* ldsl, int tid, int G, float PRUNE, int pir) {
;     ...
;         BLK_BAR();
;         int nvmax = 0;
; #pragma unroll
;         for (int w_ = 0; w_ < 8; ++w_) { const int v_ = nvs[w_]; nvmax = v_ > nvmax ? v_ : nvmax; }
;         nvmax = __builtin_amdgcn_readfirstlane(nvmax);
;         if (nvmax >= 56) {
;     ...
;             DMA_TILE(QB0 - it - 4);
;             const int kt = qb - it;
;             if (it <= nvalid) {
;                 const unsigned char* tb = lds + ((kt + 120) % 12) * 10240;
;                 const float off = it == 0 ? 0.f : __int_as_float(__builtin_amdgcn_readlane(__float_as_int(offv), it - 1));
;                 bf16x8 kf[4]; f32x4 ck[4];
; #pragma unroll
;                 for (int ks = 0; ks < 4; ++ks) kf[ks] = *(const bf16x8*)(tb + koff + (((2 * ks + hi) ^ ksw) << 4));
; #pragma unroll
;                 for (int blk = 0; blk < 2; ++blk)
; #pragma unroll
;                     for (int s = 0; s < 2; ++s) vf[blk][s] = *(const bf16x8*)(tb + voff + blk * 2048 + (((2 * s + hi) ^ vsw) << 4));
; #pragma unroll
;                 for (int s = 0; s < 2; ++s) { ck[2 * s] = *(const f32x4*)(tb + 8192 + wvu * 256 + (16 * s + 8 * hi) * 4); ck[2 * s + 1] = *(const f32x4*)(tb + 8192 + wvu * 256 + (16 * s + 8 * hi) * 4 + 16); }
;                 const float cb = cq + off;
; #pragma unroll
;                 for (int i = 0; i < 16; ++i) sc[i] = cb;
; #pragma unroll
;                 for (int ks = 0; ks < 4; ++ks) sc = MFMA32(kf[ks], qf[ks], sc);
;                 float mx = -INFINITY;
; #pragma unroll
;                 for (int r = 0; r < 16; ++r) { const int kl = 16 * (r >> 3) + 8 * hi + (r & 7);
;                     float v = sc[r] - ck[r >> 2][r & 3];
;                     if (kt == qb && kl > r32) v = -INFINITY;
;                     sc[r] = v; mx = fmaxf(mx, v); }
;                 { const auto rr = __builtin_amdgcn_permlane32_swap(__float_as_uint(mx), __float_as_uint(mx), false, false);
;                   mx = fmaxf(__uint_as_float(rr[0]), __uint_as_float(rr[1])); }
;                 const float mnew = fmaxf(mrun, mx); alpha = __builtin_amdgcn_exp2f(mrun - mnew); mrun = mnew;
; #pragma unroll
;                 for (int r = 0; r < 16; ++r) sc[r] = __builtin_amdgcn_exp2f(sc[r] - mnew);
;                 if (stag) pend = true; else ATT_TAIL();
.LBB0_740:
	s_or_b64 exec, exec, s[0:1]
	s_waitcnt lgkmcnt(0)
	s_barrier
	v_mov_b32_e32 v118, 0x1e000
	ds_read_b128 v[120:123], v118
	ds_read_b128 v[116:119], v118 offset:16
	s_mov_b64 s[0:1], -1
	s_waitcnt lgkmcnt(0)
	v_max3_i32 v4, v120, v121, v122
	v_max3_i32 v4, v4, v123, v116
	v_max3_i32 v4, v4, v117, v118
	v_max3_i32 v2, v4, v119, 0
	s_nop 0
	v_readfirstlane_b32 s5, v2
	s_cmp_gt_i32 s5, 55
	s_cbranch_scc1 .LBB0_765
	s_cmp_gt_i32 s5, -1
	s_waitcnt vmcnt(6)
	s_waitcnt lgkmcnt(0)
	s_barrier
	s_cbranch_scc0 .LBB0_744
	s_max_i32 s0, s33, 4
	s_addk_i32 s33, 0x74
	s_add_i32 s2, s0, -4
	s_mul_hi_i32 s0, s33, 0x2aaaaaab
	s_lshr_b32 s1, s0, 31
	s_lshr_b32 s0, s0, 1
	s_add_i32 s0, s0, s1
	s_mul_i32 s0, s0, 12
	s_sub_i32 s33, s33, s0
	v_mad_u64_u32 v[2:3], s[0:1], v168, s2, 0
	s_mulk_i32 s33, 0x2800
	s_add_i32 s0, s33, 0
	v_lshl_add_u64 v[2:3], v[2:3], 1, v[172:173]
	s_add_i32 m0, s0, s84
	s_lshl_b32 s62, s2, 5
	s_add_i32 s0, s0, s85
	global_load_lds_dwordx4 v[2:3], off
	v_lshl_add_u64 v[2:3], s[62:63], 2, v[166:167]
	s_add_i32 m0, s0, 0x2000
	v_add_u32_e32 v4, 0x78, v88
	global_load_lds_dword v[2:3], off
	v_mul_hi_i32 v2, v4, s89
	v_lshrrev_b32_e32 v3, 31, v2
	v_lshrrev_b32_e32 v2, 1, v2
	v_add_u32_e32 v2, v2, v3
	v_mul_lo_u32 v2, v2, 12
	v_sub_u32_e32 v2, v4, v2
	v_mad_i32_i24 v26, v2, s90, 0
	v_add_u32_e32 v27, v26, v169
	v_add_u32_e32 v2, v27, v214
	v_add_u32_e32 v3, v27, v215
	ds_read_b128 v[18:21], v2
	ds_read_b128 v[22:25], v3
	v_add_f32_e32 v2, 0, v90
	v_mov_b32_e32 v3, v2
	v_mov_b32_e32 v4, v2
	v_mov_b32_e32 v5, v2
	v_mov_b32_e32 v6, v2
	v_mov_b32_e32 v7, v2
	v_mov_b32_e32 v8, v2
	v_mov_b32_e32 v9, v2
	v_mov_b32_e32 v10, v2
	v_mov_b32_e32 v11, v2
	v_mov_b32_e32 v12, v2
	v_mov_b32_e32 v13, v2
	v_mov_b32_e32 v14, v2
	v_mov_b32_e32 v15, v2
	v_mov_b32_e32 v16, v2
	v_mov_b32_e32 v17, v2
	v_add3_u32 v34, v26, s85, v207
	s_andn2_b64 vcc, exec, s[38:39]
	s_waitcnt lgkmcnt(0)
	v_mfma_f32_32x32x16_bf16 v[2:17], v[18:21], v[50:53], v[2:17]
	v_add_u32_e32 v18, v27, v216
	ds_read_b128 v[18:21], v18
	v_mfma_f32_32x32x16_bf16 v[2:17], v[22:25], v[54:57], v[2:17]
	v_add_u32_e32 v22, v27, v217
	ds_read_b128 v[22:25], v22
	v_add_u32_e32 v27, v26, v196
	v_add_u32_e32 v28, v27, v218
	v_add_u32_e32 v27, v27, v219
	ds_read_b128 v[74:77], v28 offset:4096
	ds_read_b128 v[70:73], v28 offset:6144
	ds_read_b128 v[78:81], v27 offset:4096
	ds_read_b128 v[66:69], v27 offset:6144
	s_waitcnt lgkmcnt(0)
	v_mfma_f32_32x32x16_bf16 v[2:17], v[18:21], v[58:61], v[2:17]
	ds_read_b128 v[18:21], v34 offset:8192
	ds_read_b128 v[26:29], v34 offset:8208
	ds_read_b128 v[30:33], v34 offset:8256
	ds_read_b128 v[34:37], v34 offset:8272
	v_mfma_f32_32x32x16_bf16 v[2:17], v[22:25], v[62:65], v[2:17]
	s_waitcnt lgkmcnt(0)
	s_nop 10
	v_sub_f32_e32 v2, v2, v18
	v_sub_f32_e32 v3, v3, v19
	v_cndmask_b32_e64 v2, v2, v223, s[40:41]
	v_cndmask_b32_e64 v3, v223, v3, s[42:43]
	v_sub_f32_e32 v4, v4, v20
	v_sub_f32_e32 v5, v5, v21
	v_max3_f32 v18, v2, s88, v3
	v_cndmask_b32_e64 v4, v4, v223, s[44:45]
	v_cndmask_b32_e64 v5, v5, v223, s[26:27]
	v_sub_f32_e32 v6, v6, v26
	v_sub_f32_e32 v7, v7, v27
	v_max3_f32 v18, v18, v4, v5
	v_cndmask_b32_e64 v6, v6, v223, s[28:29]
	v_cndmask_b32_e64 v7, v7, v223, s[30:31]
	v_sub_f32_e32 v8, v8, v28
	v_sub_f32_e32 v9, v9, v29
	v_max3_f32 v18, v18, v6, v7
	v_cndmask_b32_e64 v8, v8, v223, s[34:35]
	v_cndmask_b32_e64 v9, v9, v223, s[74:75]
	v_sub_f32_e32 v10, v10, v30
	v_sub_f32_e32 v11, v11, v31
	v_max3_f32 v18, v18, v8, v9
	v_cndmask_b32_e64 v10, v10, v223, s[76:77]
	v_cndmask_b32_e64 v11, v11, v223, s[82:83]
	v_sub_f32_e32 v12, v12, v32
	v_sub_f32_e32 v13, v13, v33
	v_max3_f32 v18, v18, v10, v11
	v_cndmask_b32_e64 v12, v12, v223, s[70:71]
	v_cndmask_b32_e64 v13, v13, v223, s[78:79]
	v_sub_f32_e32 v14, v14, v34
	v_sub_f32_e32 v15, v15, v35
	v_max3_f32 v18, v18, v12, v13
	v_cndmask_b32_e64 v14, v14, v223, s[20:21]
	v_cndmask_b32_e64 v15, v15, v223, s[22:23]
	v_sub_f32_e32 v16, v16, v36
	v_sub_f32_e32 v17, v17, v37
	v_max3_f32 v18, v18, v14, v15
	v_cndmask_b32_e64 v16, v16, v223, s[24:25]
	v_cndmask_b32_e64 v17, v17, v223, s[52:53]
	v_max3_f32 v18, v18, v16, v17
	v_mov_b32_e32 v19, v18
	s_nop 1
	v_permlane32_swap_b32_e32 v18, v19
	v_max3_f32 v94, v18, v19, s88
	v_sub_f32_e32 v2, v2, v94
	v_exp_f32_e32 v92, v2
	v_sub_f32_e32 v2, v3, v94
	v_exp_f32_e32 v37, v2
	v_sub_f32_e32 v2, v4, v94
	v_exp_f32_e32 v40, v2
	v_sub_f32_e32 v2, v5, v94
	v_exp_f32_e32 v44, v2
	v_sub_f32_e32 v2, v6, v94
	v_exp_f32_e32 v38, v2
	v_sub_f32_e32 v2, v7, v94
	v_exp_f32_e32 v41, v2
	v_sub_f32_e32 v2, v8, v94
	v_exp_f32_e32 v45, v2
	v_sub_f32_e32 v2, v9, v94
	v_exp_f32_e32 v46, v2
	v_sub_f32_e32 v2, v10, v94
	v_exp_f32_e32 v47, v2
	v_sub_f32_e32 v2, v11, v94
	v_exp_f32_e32 v48, v2
	v_sub_f32_e32 v2, v12, v94
	v_exp_f32_e32 v49, v2
	v_sub_f32_e32 v2, v13, v94
	v_exp_f32_e32 v35, v2
	v_sub_f32_e32 v2, v14, v94
	v_exp_f32_e32 v36, v2
	v_sub_f32_e32 v2, v15, v94
	v_exp_f32_e32 v39, v2
	v_sub_f32_e32 v2, v16, v94
	v_sub_f32_e32 v18, 0xff800000, v94
	v_exp_f32_e32 v42, v2
	v_sub_f32_e32 v2, v17, v94
	v_exp_f32_e32 v43, v2
	v_exp_f32_e32 v34, v18
	v_cndmask_b32_e64 v2, 0, 1, s[38:39]
	v_cmp_ne_u32_e64 s[56:57], 1, v2
	s_cbranch_vccnz .LBB0_745
	v_add_f32_e32 v2, 0, v92
	v_add_f32_e32 v2, v37, v2
	v_add_f32_e32 v2, v40, v2
	v_add_f32_e32 v2, v44, v2
	v_add_f32_e32 v2, v38, v2
	v_add_f32_e32 v2, v41, v2
	v_add_f32_e32 v2, v45, v2
	v_add_f32_e32 v2, v46, v2
	v_add_f32_e32 v2, v47, v2
	v_add_f32_e32 v2, v48, v2
	v_add_f32_e32 v2, v49, v2
	v_add_f32_e32 v2, v35, v2
	v_add_f32_e32 v2, v36, v2
	v_add_f32_e32 v2, v39, v2
	v_cmp_neq_f32_e32 vcc, 1.0, v34
	v_add_f32_e32 v2, v42, v2
	s_cmp_lg_u64 vcc, 0
	v_add_f32_e32 v93, v43, v2
	v_mul_f32_e32 v2, 0, v34
	s_cselect_b64 vcc, -1, 0
	v_cndmask_b32_e32 v2, 0, v2, vcc
	v_cvt_pk_bf16_f32 v96, v92, v37
	v_cvt_pk_bf16_f32 v97, v40, v44
	v_cvt_pk_bf16_f32 v98, v38, v41
	v_cvt_pk_bf16_f32 v99, v45, v46
	v_mov_b32_e32 v3, v2
	v_mov_b32_e32 v4, v2
	v_mov_b32_e32 v5, v2
	v_mov_b32_e32 v6, v2
	v_mov_b32_e32 v7, v2
	v_mov_b32_e32 v8, v2
	v_mov_b32_e32 v9, v2
	v_mov_b32_e32 v10, v2
	v_mov_b32_e32 v11, v2
	v_mov_b32_e32 v12, v2
	v_mov_b32_e32 v13, v2
	v_mov_b32_e32 v14, v2
	v_mov_b32_e32 v15, v2
	v_mov_b32_e32 v16, v2
	v_mov_b32_e32 v17, v2
	v_cvt_pk_bf16_f32 v100, v47, v48
	v_cvt_pk_bf16_f32 v101, v49, v35
	v_mfma_f32_32x32x16_bf16 v[18:33], v[74:77], v[96:99], v[2:17]
	v_cvt_pk_bf16_f32 v102, v36, v39
	v_cvt_pk_bf16_f32 v103, v42, v43
	v_fmac_f32_e32 v93, 0, v34
	v_mfma_f32_32x32x16_bf16 v[2:17], v[70:73], v[96:99], v[2:17]
	v_mfma_f32_32x32x16_bf16 v[18:33], v[78:81], v[100:103], v[18:33]
	v_mfma_f32_32x32x16_bf16 v[2:17], v[66:69], v[100:103], v[2:17]
	s_branch .LBB0_746
